# v59 + RCM: retention contrib MFMA fragment reads issued up front with counted lgkmcnt waits
# baseline (speedup 1.0000x reference)
; #define LAS __attribute__((address_space(3)))
; __device__ __forceinline__ int crow16(int r, int hi) { return (r & 3) + 8 * (r >> 2) + 4 * hi; }
; template <int KSTEPS> __device__ __forceinline__ void mma32(f32x16& acc, const lds_t* A, int lda, const lds_t* B, int ldb, int lane) {
;     const lds_t* ap = A + (lane & 31) * lda + (lane >> 5) * 16; const lds_t* bp = B + (lane & 31) * ldb + (lane >> 5) * 16;
; #pragma unroll
;     for (int k = 0; k < KSTEPS; ++k) acc = __builtin_amdgcn_mfma_f32_32x32x16_bf16(*(const LAS bf16x8*)(ap + 32 * k), *(const LAS bf16x8*)(bp + 32 * k), acc, 0, 0, 0);
; }
; __device__ __forceinline__ void ret_contrib_unit(int unit, int next_unit, RetKV& pre, const bf16* RK, const bf16* RV, const float* decay_l, float* RETC, lds_t* lds, int tid, int lane, int wave) {
;     ...
;     { const int dir = wave >> 2, dt = (wave >> 1) & 1, vt = wave & 1; f32x16 acc = {};
;         mma32<8>(acc, (dir ? Kbt : Kft) + 32 * dt * RT_LDK, RT_LDK, Vt + 32 * vt * RT_LDK, RT_LDK, lane);
;         float* dst = RETC + ((size_t)unit * 2 + dir) * 4096 + (32 * vt + (lane & 31));
; #pragma unroll
;         for (int r = 0; r < 16; ++r) dst[(size_t)(32 * dt + crow16(r, lane >> 5)) * 64] = acc[r]; }
.LBB0_543:
	ds_read_b128 v[44:47], v33
	ds_read_b128 v[76:79], v34 offset:34816
	ds_read_b128 v[48:51], v33 offset:32
	ds_read_b128 v[80:83], v34 offset:34848
	ds_read_b128 v[52:55], v33 offset:64
	ds_read_b128 v[84:87], v34 offset:34880
	ds_read_b128 v[56:59], v33 offset:96
	ds_read_b128 v[88:91], v34 offset:34912
	ds_read_b128 v[60:63], v33 offset:128
	ds_read_b128 v[92:95], v34 offset:34944
	ds_read_b128 v[64:67], v33 offset:160
	ds_read_b128 v[96:99], v34 offset:34976
	ds_read_b128 v[68:71], v33 offset:192
	ds_read_b128 v[100:103], v34 offset:35008
	ds_read_b128 v[72:75], v33 offset:224
	ds_read_b128 v[104:107], v34 offset:35040
	s_mov_b32 s1, 0x6800000
	s_waitcnt lgkmcnt(14)
	v_mfma_f32_32x32x16_bf16 v[2:17], v[44:47], v[76:79], 0
	s_waitcnt lgkmcnt(12)
	v_mfma_f32_32x32x16_bf16 v[2:17], v[48:51], v[80:83], v[2:17]
	s_waitcnt lgkmcnt(10)
	v_mfma_f32_32x32x16_bf16 v[2:17], v[52:55], v[84:87], v[2:17]
	s_waitcnt lgkmcnt(8)
	v_mfma_f32_32x32x16_bf16 v[2:17], v[56:59], v[88:91], v[2:17]
	s_waitcnt lgkmcnt(6)
	v_mfma_f32_32x32x16_bf16 v[2:17], v[60:63], v[92:95], v[2:17]
	s_waitcnt lgkmcnt(4)
	v_mfma_f32_32x32x16_bf16 v[2:17], v[64:67], v[96:99], v[2:17]
	s_waitcnt lgkmcnt(2)
	v_mfma_f32_32x32x16_bf16 v[2:17], v[68:71], v[100:103], v[2:17]
	s_waitcnt lgkmcnt(0)
	v_mfma_f32_32x32x16_bf16 v[2:17], v[72:75], v[104:107], v[2:17]
	v_lshl_add_u64 v[36:37], v[20:21], 0, v[0:1]
	v_add_co_u32_e32 v38, vcc, s1, v36
	s_mov_b32 s1, 0x6801000
	s_nop 0
	v_addc_co_u32_e32 v39, vcc, 0, v37, vcc
	v_add_co_u32_e32 v36, vcc, s1, v36
	s_nop 1
	v_addc_co_u32_e32 v37, vcc, 0, v37, vcc
	s_nop 2
	global_store_dword v[36:37], v2, off offset:-4096
	global_store_dword v[38:39], v3, off offset:256
	global_store_dword v[38:39], v4, off offset:512
	v_lshl_add_u64 v[2:3], v[20:21], 0, v[28:29]
	global_store_dword v[2:3], v5, off
	global_store_dword v[38:39], v6, off offset:2048
	global_store_dword v[38:39], v7, off offset:2304
	global_store_dword v[38:39], v8, off offset:2560
	v_lshl_add_u64 v[2:3], v[20:21], 0, v[26:27]
	global_store_dword v[2:3], v9, off
	global_store_dword v[36:37], v10, off
	global_store_dword v[36:37], v11, off offset:256
	global_store_dword v[36:37], v12, off offset:512
	v_lshl_add_u64 v[2:3], v[20:21], 0, v[24:25]
	global_store_dword v[2:3], v13, off
	global_store_dword v[36:37], v14, off offset:2048
	global_store_dword v[36:37], v15, off offset:2304
	global_store_dword v[36:37], v16, off offset:2560
	v_lshl_add_u64 v[2:3], v[20:21], 0, v[22:23]
	v_lshl_add_u64 v[20:21], v[20:21], 0, s[8:9]
	s_and_b64 vcc, exec, s[10:11]
	global_store_dword v[2:3], v17, off
	s_barrier
	s_cbranch_vccnz .LBB0_549
